# residual-GEMM epilogue: x loads issued in 3 batches (4+12+16) instead of 32 serialized load-wait-fma-store round trips; same fma
# speedup vs baseline: 1.0863x; 1.0193x over previous
; #define PG8_STAGE(bufoff, gbase, voff) do { _Pragma("unroll") for (int _i = 0; _i < 2; ++_i) \
;         __builtin_amdgcn_global_load_lds((const unsigned*)((const char*)(gbase) + (voff)[_i]), (LAS unsigned*)(lds + (bufoff) + ldsw + _i * 8192), 16, 0, 0); } while (0)
; #define PG8_LDA(dst, b, h) do { _Pragma("unroll") for (int m = 0; m < 4; ++m) _Pragma("unroll") for (int k = 0; k < 2; ++k) dst[m][k] = *(const LAS bf16x8*)(lds + PG8_SA(b, h) + aoff + m * 2048 + k * 1024); } while (0)
; #define PG8_LDB(dst, b, h) do { _Pragma("unroll") for (int n = 0; n < 2; ++n) _Pragma("unroll") for (int k = 0; k < 2; ++k) dst[n][k] = *(const LAS bf16x8*)(lds + PG8_SB(b, h) + boff + n * 2048 + k * 1024); } while (0)
; #define PG8_MMA(ai, bj, At, Bt) do { __builtin_amdgcn_s_setprio(1); _Pragma("unroll") for (int m = 0; m < 4; ++m) _Pragma("unroll") for (int n = 0; n < 2; ++n) _Pragma("unroll") for (int k = 0; k < 2; ++k) \
;         acc[ai][bj][m][n] = __builtin_amdgcn_mfma_f32_16x16x32_bf16(Bt[n][k], At[m][k], acc[ai][bj][m][n], 0, 0, 0); __builtin_amdgcn_s_setprio(0); } while (0)
; #define PG8_WAIT_V(n) asm volatile("s_waitcnt vmcnt(" #n ")" ::: "memory")
; #define PG8_WAIT_L(n) asm volatile("s_waitcnt lgkmcnt(" #n ")" ::: "memory")
; #define PG8_BAR __builtin_amdgcn_s_barrier()
; #define PG8_SCHED __builtin_amdgcn_sched_barrier(0)
; template <class Epi, class Sched>
; __device__ __forceinline__ void gemm_phase(LAS unsigned char* lds, const Gemm g, const Sched& S, const Epi& E, const Ids I) {
;     ...
;             PG8_LDB(B0, 0, 0); PG8_SCHED; PG8_LDA(At, 0, 0); PG8_STAGE(PG8_SA(1, 1), a1 + hstep, voffA);
;             PG8_WAIT_L(8); PG8_BAR; PG8_WAIT_L(0); PG8_MMA(0, 0, At, B0); PG8_BAR; PG8_SCHED;
;             PG8_LDB(B1, 0, 1); PG8_STAGE(PG8_SB(0, 0), b2, voffB);
;             PG8_BAR; PG8_WAIT_L(0); PG8_MMA(0, 1, At, B1); PG8_BAR;
;             PG8_LDA(At, 0, 1); PG8_STAGE(PG8_SA(0, 0), a2, voffA);
;             PG8_BAR; PG8_WAIT_L(0); PG8_MMA(1, 0, At, B0); PG8_BAR; PG8_SCHED;
;             PG8_STAGE(PG8_SB(0, 1), b2 + hstep, voffB);
;             PG8_WAIT_V(6); PG8_BAR; PG8_MMA(1, 1, At, B1); PG8_BAR;
.LBB0_374:
	s_add_i32 s44, s16, 2
	s_add_u32 s18, s14, 0x80
	s_addc_u32 s17, s15, 0
	s_add_i32 s45, 0, 0x10000
	v_add_u32_e32 v131, s45, v168
	ds_read_b128 v[138:141], v131
	ds_read_b128 v[152:155], v131 offset:1024
	ds_read_b128 v[156:159], v131 offset:2048
	ds_read_b128 v[160:163], v131 offset:3072
	s_cmp_eq_u32 s34, s16
	s_cselect_b32 s16, s6, s18
	s_cselect_b32 s17, s7, s17
	s_cselect_b32 s19, s9, s43
	s_cselect_b32 s18, s8, s42
	v_lshl_add_u64 v[142:143], s[14:15], 0, v[134:135]
	s_add_i32 m0, s25, 0xc000
	ds_read_b128 v[164:167], v170
	ds_read_b128 v[188:191], v170 offset:1024
	ds_read_b128 v[192:195], v170 offset:2048
	ds_read_b128 v[196:199], v170 offset:3072
	ds_read_b128 v[200:203], v170 offset:4096
	ds_read_b128 v[204:207], v170 offset:5120
	ds_read_b128 v[208:211], v170 offset:6144
	ds_read_b128 v[212:215], v170 offset:7168
	global_load_lds_dwordx4 v[142:143], off
	v_lshl_add_u64 v[142:143], s[14:15], 0, v[136:137]
	s_add_i32 m0, s25, 0xe000
	s_nop 0
	global_load_lds_dwordx4 v[142:143], off
	s_waitcnt lgkmcnt(8)
	s_barrier
	s_waitcnt lgkmcnt(0)
	s_setprio 1
	s_waitcnt lgkmcnt(0)
	v_mfma_f32_16x16x32_bf16 v[124:127], v[138:141], v[164:167], v[124:127]
	v_mfma_f32_16x16x32_bf16 v[120:123], v[156:159], v[164:167], v[120:123]
	v_mfma_f32_16x16x32_bf16 v[108:111], v[138:141], v[192:195], v[108:111]
	v_mfma_f32_16x16x32_bf16 v[104:107], v[156:159], v[192:195], v[104:107]
	v_mfma_f32_16x16x32_bf16 v[92:95], v[138:141], v[200:203], v[92:95]
	v_mfma_f32_16x16x32_bf16 v[88:91], v[156:159], v[200:203], v[88:91]
	v_mfma_f32_16x16x32_bf16 v[76:79], v[138:141], v[208:211], v[76:79]
	v_mfma_f32_16x16x32_bf16 v[72:75], v[156:159], v[208:211], v[72:75]
	v_mfma_f32_16x16x32_bf16 v[124:127], v[152:155], v[188:191], v[124:127]
	v_mfma_f32_16x16x32_bf16 v[120:123], v[160:163], v[188:191], v[120:123]
	v_mfma_f32_16x16x32_bf16 v[108:111], v[152:155], v[196:199], v[108:111]
	v_mfma_f32_16x16x32_bf16 v[104:107], v[160:163], v[196:199], v[104:107]
	v_mfma_f32_16x16x32_bf16 v[92:95], v[152:155], v[204:207], v[92:95]
	v_mfma_f32_16x16x32_bf16 v[88:91], v[160:163], v[204:207], v[88:91]
	v_mfma_f32_16x16x32_bf16 v[76:79], v[152:155], v[212:215], v[76:79]
	v_mfma_f32_16x16x32_bf16 v[72:75], v[160:163], v[212:215], v[72:75]
	s_setprio 0
	s_barrier
	s_add_i32 s46, 0, 0x14000
	s_add_i32 s45, s45, s24
	v_add_u32_e32 v131, s46, v168
	v_lshl_add_u64 v[142:143], s[18:19], 0, v[144:145]
	s_mov_b32 m0, s45
	ds_read_b128 v[216:219], v131
	ds_read_b128 v[220:223], v131 offset:1024
	ds_read_b128 v[224:227], v131 offset:2048
	ds_read_b128 v[228:231], v131 offset:3072
	global_load_lds_dwordx4 v[142:143], off
	v_lshl_add_u64 v[172:173], s[18:19], 0, v[128:129]
	s_add_i32 m0, s45, 0x2000
	s_nop 0
	global_load_lds_dwordx4 v[172:173], off
	s_barrier
	s_waitcnt lgkmcnt(0)
	s_setprio 1
	s_waitcnt lgkmcnt(0)
	v_mfma_f32_16x16x32_bf16 v[116:119], v[216:219], v[164:167], v[116:119]
	v_mfma_f32_16x16x32_bf16 v[112:115], v[224:227], v[164:167], v[112:115]
	v_mfma_f32_16x16x32_bf16 v[100:103], v[216:219], v[192:195], v[100:103]
	v_mfma_f32_16x16x32_bf16 v[96:99], v[224:227], v[192:195], v[96:99]
	v_mfma_f32_16x16x32_bf16 v[84:87], v[216:219], v[200:203], v[84:87]
	v_mfma_f32_16x16x32_bf16 v[80:83], v[224:227], v[200:203], v[80:83]
	v_mfma_f32_16x16x32_bf16 v[68:71], v[216:219], v[208:211], v[68:71]
	v_mfma_f32_16x16x32_bf16 v[64:67], v[224:227], v[208:211], v[64:67]
	v_mfma_f32_16x16x32_bf16 v[116:119], v[220:223], v[188:191], v[116:119]
	v_mfma_f32_16x16x32_bf16 v[112:115], v[228:231], v[188:191], v[112:115]
	v_mfma_f32_16x16x32_bf16 v[100:103], v[220:223], v[196:199], v[100:103]
	v_mfma_f32_16x16x32_bf16 v[96:99], v[228:231], v[196:199], v[96:99]
	v_mfma_f32_16x16x32_bf16 v[84:87], v[220:223], v[204:207], v[84:87]
	v_mfma_f32_16x16x32_bf16 v[80:83], v[228:231], v[204:207], v[80:83]
	v_mfma_f32_16x16x32_bf16 v[68:71], v[220:223], v[212:215], v[68:71]
	v_mfma_f32_16x16x32_bf16 v[64:67], v[228:231], v[212:215], v[64:67]
	s_setprio 0
	s_mov_b32 m0, s25
	v_lshl_add_u64 v[176:177], s[16:17], 0, v[144:145]
	s_barrier
	ds_read_b128 v[164:167], v170 offset:16384
	ds_read_b128 v[188:191], v170 offset:17408
	ds_read_b128 v[192:195], v170 offset:18432
	ds_read_b128 v[196:199], v170 offset:19456
	ds_read_b128 v[200:203], v170 offset:20480
	ds_read_b128 v[204:207], v170 offset:21504
	ds_read_b128 v[208:211], v170 offset:22528
	ds_read_b128 v[212:215], v170 offset:23552
	global_load_lds_dwordx4 v[176:177], off
	v_lshl_add_u64 v[178:179], s[16:17], 0, v[128:129]
	s_mov_b32 m0, s26
	s_nop 0
	global_load_lds_dwordx4 v[178:179], off
	s_barrier
	s_waitcnt lgkmcnt(0)
	s_setprio 1
	s_waitcnt lgkmcnt(0)
	v_mfma_f32_16x16x32_bf16 v[60:63], v[138:141], v[164:167], v[60:63]
	v_mfma_f32_16x16x32_bf16 v[56:59], v[156:159], v[164:167], v[56:59]
	v_mfma_f32_16x16x32_bf16 v[44:47], v[138:141], v[192:195], v[44:47]
	v_mfma_f32_16x16x32_bf16 v[40:43], v[156:159], v[192:195], v[40:43]
	v_mfma_f32_16x16x32_bf16 v[28:31], v[138:141], v[200:203], v[28:31]
	v_mfma_f32_16x16x32_bf16 v[24:27], v[156:159], v[200:203], v[24:27]
	v_mfma_f32_16x16x32_bf16 v[12:15], v[138:141], v[208:211], v[12:15]
	v_mfma_f32_16x16x32_bf16 v[8:11], v[156:159], v[208:211], v[8:11]
	v_mfma_f32_16x16x32_bf16 v[60:63], v[152:155], v[188:191], v[60:63]
	v_mfma_f32_16x16x32_bf16 v[56:59], v[160:163], v[188:191], v[56:59]
	v_mfma_f32_16x16x32_bf16 v[44:47], v[152:155], v[196:199], v[44:47]
	v_mfma_f32_16x16x32_bf16 v[40:43], v[160:163], v[196:199], v[40:43]
	v_mfma_f32_16x16x32_bf16 v[28:31], v[152:155], v[204:207], v[28:31]
	v_mfma_f32_16x16x32_bf16 v[24:27], v[160:163], v[204:207], v[24:27]
	v_mfma_f32_16x16x32_bf16 v[12:15], v[152:155], v[212:215], v[12:15]
	v_mfma_f32_16x16x32_bf16 v[8:11], v[160:163], v[212:215], v[8:11]
	s_setprio 0
	s_barrier
; #define PG8_STAGE(bufoff, gbase, voff) do { _Pragma("unroll") for (int _i = 0; _i < 2; ++_i) \
;         __builtin_amdgcn_global_load_lds((const unsigned*)((const char*)(gbase) + (voff)[_i]), (LAS unsigned*)(lds + (bufoff) + ldsw + _i * 8192), 16, 0, 0); } while (0)
; #define PG8_LDA(dst, b, h) do { _Pragma("unroll") for (int m = 0; m < 4; ++m) _Pragma("unroll") for (int k = 0; k < 2; ++k) dst[m][k] = *(const LAS bf16x8*)(lds + PG8_SA(b, h) + aoff + m * 2048 + k * 1024); } while (0)
; #define PG8_LDB(dst, b, h) do { _Pragma("unroll") for (int n = 0; n < 2; ++n) _Pragma("unroll") for (int k = 0; k < 2; ++k) dst[n][k] = *(const LAS bf16x8*)(lds + PG8_SB(b, h) + boff + n * 2048 + k * 1024); } while (0)
; #define PG8_MMA(ai, bj, At, Bt) do { __builtin_amdgcn_s_setprio(1); _Pragma("unroll") for (int m = 0; m < 4; ++m) _Pragma("unroll") for (int n = 0; n < 2; ++n) _Pragma("unroll") for (int k = 0; k < 2; ++k) \
;         acc[ai][bj][m][n] = __builtin_amdgcn_mfma_f32_16x16x32_bf16(Bt[n][k], At[m][k], acc[ai][bj][m][n], 0, 0, 0); __builtin_amdgcn_s_setprio(0); } while (0)
; #define PG8_WAIT_V(n) asm volatile("s_waitcnt vmcnt(" #n ")" ::: "memory")
; #define PG8_WAIT_L(n) asm volatile("s_waitcnt lgkmcnt(" #n ")" ::: "memory")
; #define PG8_BAR __builtin_amdgcn_s_barrier()
; #define PG8_SCHED __builtin_amdgcn_sched_barrier(0)
; template <class Epi, class Sched>
; __device__ __forceinline__ void gemm_phase(LAS unsigned char* lds, const Gemm g, const Sched& S, const Epi& E, const Ids I) {
;     ...
;             PG8_WAIT_V(6); PG8_BAR; PG8_MMA(1, 1, At, B1); PG8_BAR;
;             PG8_LDB(B0, 1, 0); PG8_SCHED; PG8_LDA(At, 1, 0); PG8_STAGE(PG8_SA(0, 1), a2 + hstep, voffA);
;             PG8_WAIT_L(8); PG8_BAR; PG8_WAIT_L(0); PG8_MMA(0, 0, At, B0); PG8_BAR; PG8_SCHED;
;             PG8_LDB(B1, 1, 1); PG8_STAGE(PG8_SB(1, 0), b3, voffB);
;             PG8_BAR; PG8_WAIT_L(0); PG8_MMA(0, 1, At, B1); PG8_BAR;
;             PG8_LDA(At, 1, 1); PG8_STAGE(PG8_SA(1, 0), a3, voffA);
;             PG8_BAR; PG8_WAIT_L(0); PG8_MMA(1, 0, At, B0); PG8_BAR; PG8_SCHED;
	s_add_u32 s18, s18, s54
	s_addc_u32 s19, s19, 0
	s_add_i32 s45, s46, s24
	v_lshl_add_u64 v[180:181], s[18:19], 0, v[144:145]
	s_mov_b32 m0, s45
	v_lshl_add_u64 v[182:183], s[18:19], 0, v[128:129]
	global_load_lds_dwordx4 v[180:181], off
	s_add_i32 m0, s45, 0x2000
	s_nop 0
	global_load_lds_dwordx4 v[182:183], off
	s_waitcnt vmcnt(6)
	s_barrier
	s_setprio 1
	v_mfma_f32_16x16x32_bf16 v[52:55], v[216:219], v[164:167], v[52:55]
	v_mfma_f32_16x16x32_bf16 v[48:51], v[224:227], v[164:167], v[48:51]
	v_mfma_f32_16x16x32_bf16 v[36:39], v[216:219], v[192:195], v[36:39]
	v_mfma_f32_16x16x32_bf16 v[32:35], v[224:227], v[192:195], v[32:35]
	v_mfma_f32_16x16x32_bf16 v[20:23], v[216:219], v[200:203], v[20:23]
	v_mfma_f32_16x16x32_bf16 v[16:19], v[224:227], v[200:203], v[16:19]
	v_mfma_f32_16x16x32_bf16 v[4:7], v[216:219], v[208:211], v[4:7]
	v_mfma_f32_16x16x32_bf16 v[0:3], v[224:227], v[208:211], v[0:3]
	v_mfma_f32_16x16x32_bf16 v[52:55], v[220:223], v[188:191], v[52:55]
	v_mfma_f32_16x16x32_bf16 v[48:51], v[228:231], v[188:191], v[48:51]
	v_mfma_f32_16x16x32_bf16 v[36:39], v[220:223], v[196:199], v[36:39]
	v_mfma_f32_16x16x32_bf16 v[32:35], v[228:231], v[196:199], v[32:35]
	v_mfma_f32_16x16x32_bf16 v[20:23], v[220:223], v[204:207], v[20:23]
	v_mfma_f32_16x16x32_bf16 v[16:19], v[228:231], v[204:207], v[16:19]
	v_mfma_f32_16x16x32_bf16 v[4:7], v[220:223], v[212:215], v[4:7]
	v_mfma_f32_16x16x32_bf16 v[0:3], v[228:231], v[212:215], v[0:3]
	s_setprio 0
	s_add_i32 s18, 0, 0x18000
	v_add_u32_e32 v131, s18, v168
	s_barrier
	ds_read_b128 v[138:141], v131
	ds_read_b128 v[152:155], v131 offset:1024
	ds_read_b128 v[156:159], v131 offset:2048
	ds_read_b128 v[160:163], v131 offset:3072
	s_add_u32 s16, s16, s54
	s_addc_u32 s17, s17, 0
	s_mov_b32 m0, s27
	v_lshl_add_u64 v[216:217], s[16:17], 0, v[144:145]
	ds_read_b128 v[164:167], v170 offset:32768
	ds_read_b128 v[188:191], v170 offset:33792
	ds_read_b128 v[192:195], v170 offset:34816
	ds_read_b128 v[196:199], v170 offset:35840
	ds_read_b128 v[200:203], v170 offset:36864
	ds_read_b128 v[204:207], v170 offset:37888
	ds_read_b128 v[208:211], v170 offset:38912
	ds_read_b128 v[212:215], v170 offset:39936
	global_load_lds_dwordx4 v[216:217], off
	v_lshl_add_u64 v[216:217], s[16:17], 0, v[128:129]
	s_mov_b32 m0, s28
	s_nop 0
	global_load_lds_dwordx4 v[216:217], off
	s_waitcnt lgkmcnt(8)
	s_barrier
	s_waitcnt lgkmcnt(0)
	s_setprio 1
	s_waitcnt lgkmcnt(0)
	v_mfma_f32_16x16x32_bf16 v[124:127], v[138:141], v[164:167], v[124:127]
	v_mfma_f32_16x16x32_bf16 v[120:123], v[156:159], v[164:167], v[120:123]
	v_mfma_f32_16x16x32_bf16 v[108:111], v[138:141], v[192:195], v[108:111]
	v_mfma_f32_16x16x32_bf16 v[104:107], v[156:159], v[192:195], v[104:107]
	v_mfma_f32_16x16x32_bf16 v[92:95], v[138:141], v[200:203], v[92:95]
	v_mfma_f32_16x16x32_bf16 v[88:91], v[156:159], v[200:203], v[88:91]
	v_mfma_f32_16x16x32_bf16 v[76:79], v[138:141], v[208:211], v[76:79]
	v_mfma_f32_16x16x32_bf16 v[72:75], v[156:159], v[208:211], v[72:75]
	v_mfma_f32_16x16x32_bf16 v[124:127], v[152:155], v[188:191], v[124:127]
	v_mfma_f32_16x16x32_bf16 v[120:123], v[160:163], v[188:191], v[120:123]
	v_mfma_f32_16x16x32_bf16 v[108:111], v[152:155], v[196:199], v[108:111]
	v_mfma_f32_16x16x32_bf16 v[104:107], v[160:163], v[196:199], v[104:107]
	v_mfma_f32_16x16x32_bf16 v[92:95], v[152:155], v[204:207], v[92:95]
	v_mfma_f32_16x16x32_bf16 v[88:91], v[160:163], v[204:207], v[88:91]
	v_mfma_f32_16x16x32_bf16 v[76:79], v[152:155], v[212:215], v[76:79]
	v_mfma_f32_16x16x32_bf16 v[72:75], v[160:163], v[212:215], v[72:75]
	s_setprio 0
	s_barrier
	s_add_i32 s16, 0, 0x1c000
	s_add_i32 s17, s18, s24
	v_add_u32_e32 v131, s16, v168
	v_lshl_add_u64 v[142:143], v[142:143], 0, s[64:65]
	s_mov_b32 m0, s17
	ds_read_b128 v[216:219], v131
	ds_read_b128 v[220:223], v131 offset:1024
	ds_read_b128 v[224:227], v131 offset:2048
	ds_read_b128 v[228:231], v131 offset:3072
	global_load_lds_dwordx4 v[142:143], off
	v_lshl_add_u64 v[142:143], v[172:173], 0, s[64:65]
	s_add_i32 m0, s17, 0x2000
	s_nop 0
	global_load_lds_dwordx4 v[142:143], off
	s_barrier
	s_waitcnt lgkmcnt(0)
	s_setprio 1
	s_waitcnt lgkmcnt(0)
	v_mfma_f32_16x16x32_bf16 v[116:119], v[216:219], v[164:167], v[116:119]
	v_mfma_f32_16x16x32_bf16 v[112:115], v[224:227], v[164:167], v[112:115]
	v_mfma_f32_16x16x32_bf16 v[100:103], v[216:219], v[192:195], v[100:103]
	v_mfma_f32_16x16x32_bf16 v[96:99], v[224:227], v[192:195], v[96:99]
	v_mfma_f32_16x16x32_bf16 v[84:87], v[216:219], v[200:203], v[84:87]
	v_mfma_f32_16x16x32_bf16 v[80:83], v[224:227], v[200:203], v[80:83]
	v_mfma_f32_16x16x32_bf16 v[68:71], v[216:219], v[208:211], v[68:71]
	v_mfma_f32_16x16x32_bf16 v[64:67], v[224:227], v[208:211], v[64:67]
	v_mfma_f32_16x16x32_bf16 v[116:119], v[220:223], v[188:191], v[116:119]
	v_mfma_f32_16x16x32_bf16 v[112:115], v[228:231], v[188:191], v[112:115]
	v_mfma_f32_16x16x32_bf16 v[100:103], v[220:223], v[196:199], v[100:103]
	v_mfma_f32_16x16x32_bf16 v[96:99], v[228:231], v[196:199], v[96:99]
	v_mfma_f32_16x16x32_bf16 v[84:87], v[220:223], v[204:207], v[84:87]
	v_mfma_f32_16x16x32_bf16 v[80:83], v[228:231], v[204:207], v[80:83]
	v_mfma_f32_16x16x32_bf16 v[68:71], v[220:223], v[212:215], v[68:71]
	v_mfma_f32_16x16x32_bf16 v[64:67], v[228:231], v[212:215], v[64:67]
	s_setprio 0
	s_mov_b32 m0, s35
	v_lshl_add_u64 v[142:143], v[176:177], 0, s[64:65]
	s_barrier
	ds_read_b128 v[164:167], v170 offset:49152
	ds_read_b128 v[188:191], v170 offset:50176
	ds_read_b128 v[192:195], v170 offset:51200
	ds_read_b128 v[196:199], v170 offset:52224
	ds_read_b128 v[200:203], v170 offset:53248
	ds_read_b128 v[204:207], v170 offset:54272
	ds_read_b128 v[208:211], v170 offset:55296
	ds_read_b128 v[212:215], v170 offset:56320
	global_load_lds_dwordx4 v[142:143], off
	v_lshl_add_u64 v[142:143], v[178:179], 0, s[64:65]
	s_mov_b32 m0, s36
	s_nop 0
	global_load_lds_dwordx4 v[142:143], off
	s_barrier
; #define PG8_STAGE(bufoff, gbase, voff) do { _Pragma("unroll") for (int _i = 0; _i < 2; ++_i) \
;         __builtin_amdgcn_global_load_lds((const unsigned*)((const char*)(gbase) + (voff)[_i]), (LAS unsigned*)(lds + (bufoff) + ldsw + _i * 8192), 16, 0, 0); } while (0)
; #define PG8_MMA(ai, bj, At, Bt) do { __builtin_amdgcn_s_setprio(1); _Pragma("unroll") for (int m = 0; m < 4; ++m) _Pragma("unroll") for (int n = 0; n < 2; ++n) _Pragma("unroll") for (int k = 0; k < 2; ++k) \
;         acc[ai][bj][m][n] = __builtin_amdgcn_mfma_f32_16x16x32_bf16(Bt[n][k], At[m][k], acc[ai][bj][m][n], 0, 0, 0); __builtin_amdgcn_s_setprio(0); } while (0)
; #define PG8_WAIT_V(n) asm volatile("s_waitcnt vmcnt(" #n ")" ::: "memory")
; #define PG8_WAIT_L(n) asm volatile("s_waitcnt lgkmcnt(" #n ")" ::: "memory")
; #define PG8_BAR __builtin_amdgcn_s_barrier()
; #define PG8_SCHED __builtin_amdgcn_sched_barrier(0)
; template <class Epi, class Sched>
; __device__ __forceinline__ void gemm_phase(LAS unsigned char* lds, const Gemm g, const Sched& S, const Epi& E, const Ids I) {
;     ...
;             PG8_BAR; PG8_WAIT_L(0); PG8_MMA(1, 0, At, B0); PG8_BAR; PG8_SCHED;
;             PG8_STAGE(PG8_SB(1, 1), b3 + hstep, voffB);
;             PG8_WAIT_V(6); PG8_BAR; PG8_MMA(1, 1, At, B1); PG8_BAR;
;         }
;         E(acc, cur, wr, wc, fr, fq);
;     __device__ __forceinline__ void operator()(const f32x4 (&acc)[2][2][4][2], const pg8::Unit& u, int wr, int wc, int fr, int fq) const {
;         const int row0 = u.pm * 256 + wr * 64 + fr, col0 = u.pn * 256 + wc * 32 + 4 * fq; const float* gp = gate + (size_t)((u.pm * 256) >> 11) * 9216 + col0;
;         f32x4 gv[2][2];
; #pragma unroll
;         for (int bj = 0; bj < 2; ++bj)
; #pragma unroll
;             for (int n = 0; n < 2; ++n) gv[bj][n] = *(const f32x4*)(gp + bj * 128 + n * 16) * scale;
; #pragma unroll
;         for (int ai = 0; ai < 2; ++ai)
; #pragma unroll
;             for (int m = 0; m < 4; ++m) { const int row = row0 + ai * 128 + m * 16; float* rowp = x + (size_t)row * D + col0;
; #pragma unroll
;                 for (int bj = 0; bj < 2; ++bj)
; #pragma unroll
;                     for (int n = 0; n < 2; ++n) { const f32x4 xv = *(const f32x4*)(rowp + bj * 128 + n * 16);
;                         *(f32x4*)(rowp + bj * 128 + n * 16) = xv + gv[bj][n] * acc[ai][bj][m][n]; }
;                 asm volatile("" ::: "memory"); }
	s_waitcnt lgkmcnt(0)
	s_setprio 1
	s_waitcnt lgkmcnt(0)
	v_mfma_f32_16x16x32_bf16 v[60:63], v[138:141], v[164:167], v[60:63]
	v_mfma_f32_16x16x32_bf16 v[56:59], v[156:159], v[164:167], v[56:59]
	v_mfma_f32_16x16x32_bf16 v[44:47], v[138:141], v[192:195], v[44:47]
	v_mfma_f32_16x16x32_bf16 v[40:43], v[156:159], v[192:195], v[40:43]
	v_mfma_f32_16x16x32_bf16 v[28:31], v[138:141], v[200:203], v[28:31]
	v_mfma_f32_16x16x32_bf16 v[24:27], v[156:159], v[200:203], v[24:27]
	v_mfma_f32_16x16x32_bf16 v[12:15], v[138:141], v[208:211], v[12:15]
	v_mfma_f32_16x16x32_bf16 v[8:11], v[156:159], v[208:211], v[8:11]
	v_mfma_f32_16x16x32_bf16 v[60:63], v[152:155], v[188:191], v[60:63]
	v_mfma_f32_16x16x32_bf16 v[56:59], v[160:163], v[188:191], v[56:59]
	v_mfma_f32_16x16x32_bf16 v[44:47], v[152:155], v[196:199], v[44:47]
	v_mfma_f32_16x16x32_bf16 v[40:43], v[160:163], v[196:199], v[40:43]
	v_mfma_f32_16x16x32_bf16 v[28:31], v[152:155], v[204:207], v[28:31]
	v_mfma_f32_16x16x32_bf16 v[24:27], v[160:163], v[204:207], v[24:27]
	v_mfma_f32_16x16x32_bf16 v[12:15], v[152:155], v[212:215], v[12:15]
	v_mfma_f32_16x16x32_bf16 v[8:11], v[160:163], v[212:215], v[8:11]
	s_setprio 0
	s_barrier
	s_add_i32 s16, s16, s24
	v_lshl_add_u64 v[138:139], v[180:181], 0, s[64:65]
	s_mov_b32 m0, s16
	s_nop 0
	global_load_lds_dwordx4 v[138:139], off
	v_lshl_add_u64 v[138:139], v[182:183], 0, s[64:65]
	s_add_i32 m0, s16, 0x2000
	s_nop 0
	global_load_lds_dwordx4 v[138:139], off
	s_waitcnt vmcnt(6)
	s_barrier
	s_setprio 1
	v_mfma_f32_16x16x32_bf16 v[52:55], v[216:219], v[164:167], v[52:55]
	v_mfma_f32_16x16x32_bf16 v[48:51], v[224:227], v[164:167], v[48:51]
	v_mfma_f32_16x16x32_bf16 v[36:39], v[216:219], v[192:195], v[36:39]
	v_mfma_f32_16x16x32_bf16 v[32:35], v[224:227], v[192:195], v[32:35]
	v_mfma_f32_16x16x32_bf16 v[20:23], v[216:219], v[200:203], v[20:23]
	v_mfma_f32_16x16x32_bf16 v[16:19], v[224:227], v[200:203], v[16:19]
	v_mfma_f32_16x16x32_bf16 v[4:7], v[216:219], v[208:211], v[4:7]
	v_mfma_f32_16x16x32_bf16 v[0:3], v[224:227], v[208:211], v[0:3]
	v_mfma_f32_16x16x32_bf16 v[52:55], v[220:223], v[188:191], v[52:55]
	v_mfma_f32_16x16x32_bf16 v[48:51], v[228:231], v[188:191], v[48:51]
	v_mfma_f32_16x16x32_bf16 v[36:39], v[220:223], v[196:199], v[36:39]
	v_mfma_f32_16x16x32_bf16 v[32:35], v[228:231], v[196:199], v[32:35]
	v_mfma_f32_16x16x32_bf16 v[20:23], v[220:223], v[204:207], v[20:23]
	v_mfma_f32_16x16x32_bf16 v[16:19], v[228:231], v[204:207], v[16:19]
	v_mfma_f32_16x16x32_bf16 v[4:7], v[220:223], v[212:215], v[4:7]
	v_mfma_f32_16x16x32_bf16 v[0:3], v[228:231], v[212:215], v[0:3]
	s_setprio 0
	s_add_u32 s14, s14, 0x100
	s_addc_u32 s15, s15, 0
	s_add_u32 s42, s42, 0x100
	s_addc_u32 s43, s43, 0
	s_cmp_ge_u32 s44, s31
	s_mov_b32 s16, s44
	s_barrier
	s_cbranch_scc0 .LBB0_374
	s_ashr_i32 s14, s40, 3
	v_lshl_or_b32 v138, s41, 8, v169
	s_mul_hi_i32 s15, s14, 0x9000
	s_mul_i32 s14, s14, 0x9000
	s_add_u32 s14, s29, s14
	v_ashrrev_i32_e32 v139, 31, v138
	s_addc_u32 s15, s30, s15
	v_lshlrev_b64 v[164:165], 2, v[138:139]
	v_lshl_add_u64 v[162:163], s[14:15], 0, v[164:165]
	global_load_dwordx4 v[192:195], v[162:163], off
	global_load_dwordx4 v[196:199], v[162:163], off offset:64
	global_load_dwordx4 v[200:203], v[162:163], off offset:512
	global_load_dwordx4 v[204:207], v[162:163], off offset:576
	v_mov_b32_e32 v131, v130
	v_lshl_add_u32 v166, s40, 8, v147
	v_ashrrev_i32_e32 v167, 31, v166
	s_mov_b32 s41, s38
	s_mov_b32 s40, s39
	s_mov_b64 s[16:17], s[8:9]
	v_lshlrev_b64 v[162:163], 12, v[166:167]
	v_lshl_add_u64 v[162:163], s[10:11], 0, v[162:163]
	v_lshl_add_u64 v[162:163], v[162:163], 0, v[164:165]
	global_load_dwordx4 v[208:211], v[162:163], off
	global_load_dwordx4 v[212:215], v[162:163], off offset:64
	global_load_dwordx4 v[216:219], v[162:163], off offset:512
	global_load_dwordx4 v[220:223], v[162:163], off offset:576
	s_waitcnt vmcnt(0)
	v_pk_mul_f32 v[158:159], v[130:131], v[194:195]
	v_pk_mul_f32 v[160:161], v[132:133], v[192:193]
	v_pk_mul_f32 v[154:155], v[130:131], v[198:199]
	v_pk_mul_f32 v[156:157], v[132:133], v[196:197]
	v_pk_mul_f32 v[142:143], v[130:131], v[202:203]
	v_pk_mul_f32 v[152:153], v[132:133], v[200:201]
	v_pk_mul_f32 v[138:139], v[130:131], v[206:207]
	v_pk_mul_f32 v[140:141], v[132:133], v[204:205]
	v_pk_fma_f32 v[126:127], v[126:127], v[158:159], v[210:211]
	v_pk_fma_f32 v[124:125], v[124:125], v[160:161], v[208:209]
	global_store_dwordx4 v[162:163], v[124:127], off
	v_pk_fma_f32 v[122:123], v[122:123], v[154:155], v[214:215]
	v_pk_fma_f32 v[120:121], v[120:121], v[156:157], v[212:213]
	global_store_dwordx4 v[162:163], v[120:123], off offset:64
	v_pk_fma_f32 v[118:119], v[118:119], v[142:143], v[218:219]
	v_pk_fma_f32 v[116:117], v[116:117], v[152:153], v[216:217]
	global_store_dwordx4 v[162:163], v[116:119], off offset:512
	v_pk_fma_f32 v[114:115], v[114:115], v[138:139], v[222:223]
	v_pk_fma_f32 v[112:113], v[112:113], v[140:141], v[220:221]
	global_store_dwordx4 v[162:163], v[112:115], off offset:576
	s_nop 1
	s_mov_b64 s[14:15], 0x10000
	v_lshl_add_u64 v[116:117], v[162:163], 0, s[14:15]
	s_mov_b64 s[14:15], 0x20000
	v_lshl_add_u64 v[118:119], v[162:163], 0, s[14:15]
	s_mov_b64 s[14:15], 0x30000
	v_lshl_add_u64 v[112:113], v[162:163], 0, s[14:15]
	global_load_dwordx4 v[192:195], v[116:117], off
	global_load_dwordx4 v[196:199], v[116:117], off offset:64
	global_load_dwordx4 v[200:203], v[116:117], off offset:512
	global_load_dwordx4 v[204:207], v[116:117], off offset:576
	global_load_dwordx4 v[208:211], v[118:119], off
	global_load_dwordx4 v[212:215], v[118:119], off offset:64
	global_load_dwordx4 v[216:219], v[118:119], off offset:512
	global_load_dwordx4 v[220:223], v[118:119], off offset:576
	global_load_dwordx4 v[224:227], v[112:113], off
	global_load_dwordx4 v[228:231], v[112:113], off offset:64
	global_load_dwordx4 v[124:127], v[112:113], off offset:512
	global_load_dwordx4 v[120:123], v[112:113], off offset:576
	s_waitcnt vmcnt(0)
;     __device__ __forceinline__ void operator()(const f32x4 (&acc)[2][2][4][2], const pg8::Unit& u, int wr, int wc, int fr, int fq) const {
;     ...
;         for (int ai = 0; ai < 2; ++ai)
; #pragma unroll
;             for (int m = 0; m < 4; ++m) { const int row = row0 + ai * 128 + m * 16; float* rowp = x + (size_t)row * D + col0;
; #pragma unroll
;                 for (int bj = 0; bj < 2; ++bj)
; #pragma unroll
;                     for (int n = 0; n < 2; ++n) { const f32x4 xv = *(const f32x4*)(rowp + bj * 128 + n * 16);
;                         *(f32x4*)(rowp + bj * 128 + n * 16) = xv + gv[bj][n] * acc[ai][bj][m][n]; }
;                 asm volatile("" ::: "memory"); }
	v_pk_fma_f32 v[110:111], v[110:111], v[158:159], v[194:195]
	v_pk_fma_f32 v[108:109], v[108:109], v[160:161], v[192:193]
	global_store_dwordx4 v[116:117], v[108:111], off
	v_pk_fma_f32 v[106:107], v[106:107], v[154:155], v[198:199]
	v_pk_fma_f32 v[104:105], v[104:105], v[156:157], v[196:197]
	global_store_dwordx4 v[116:117], v[104:107], off offset:64
	v_pk_fma_f32 v[102:103], v[102:103], v[142:143], v[202:203]
	v_pk_fma_f32 v[100:101], v[100:101], v[152:153], v[200:201]
	global_store_dwordx4 v[116:117], v[100:103], off offset:512
	v_pk_fma_f32 v[98:99], v[98:99], v[138:139], v[206:207]
	v_pk_fma_f32 v[96:97], v[96:97], v[140:141], v[204:205]
	global_store_dwordx4 v[116:117], v[96:99], off offset:576
	v_pk_fma_f32 v[94:95], v[94:95], v[158:159], v[210:211]
	v_pk_fma_f32 v[92:93], v[92:93], v[160:161], v[208:209]
	global_store_dwordx4 v[118:119], v[92:95], off
	v_pk_fma_f32 v[90:91], v[90:91], v[154:155], v[214:215]
	v_pk_fma_f32 v[88:89], v[88:89], v[156:157], v[212:213]
	global_store_dwordx4 v[118:119], v[88:91], off offset:64
	v_pk_fma_f32 v[86:87], v[86:87], v[142:143], v[218:219]
	v_pk_fma_f32 v[84:85], v[84:85], v[152:153], v[216:217]
	global_store_dwordx4 v[118:119], v[84:87], off offset:512
	v_pk_fma_f32 v[82:83], v[82:83], v[138:139], v[222:223]
	v_pk_fma_f32 v[80:81], v[80:81], v[140:141], v[220:221]
	global_store_dwordx4 v[118:119], v[80:83], off offset:576
	v_pk_fma_f32 v[78:79], v[78:79], v[158:159], v[226:227]
	v_pk_fma_f32 v[76:77], v[76:77], v[160:161], v[224:225]
	global_store_dwordx4 v[112:113], v[76:79], off
	v_pk_fma_f32 v[74:75], v[74:75], v[154:155], v[230:231]
	v_pk_fma_f32 v[72:73], v[72:73], v[156:157], v[228:229]
	global_store_dwordx4 v[112:113], v[72:75], off offset:64
	v_pk_fma_f32 v[70:71], v[70:71], v[142:143], v[126:127]
	v_pk_fma_f32 v[68:69], v[68:69], v[152:153], v[124:125]
	global_store_dwordx4 v[112:113], v[68:71], off offset:512
	v_pk_fma_f32 v[66:67], v[66:67], v[138:139], v[122:123]
	v_pk_fma_f32 v[64:65], v[64:65], v[140:141], v[120:121]
	global_store_dwordx4 v[112:113], v[64:67], off offset:576
	s_nop 1
	s_mov_b64 s[14:15], 0x80000
	v_lshl_add_u64 v[116:117], v[162:163], 0, s[14:15]
	s_mov_b64 s[14:15], 0x90000
	v_lshl_add_u64 v[118:119], v[162:163], 0, s[14:15]
	s_mov_b64 s[14:15], 0xa0000
	v_lshl_add_u64 v[112:113], v[162:163], 0, s[14:15]
	s_mov_b64 s[14:15], 0xb0000
	v_lshl_add_u64 v[114:115], v[162:163], 0, s[14:15]
	global_load_dwordx4 v[192:195], v[116:117], off
	global_load_dwordx4 v[196:199], v[116:117], off offset:64
	global_load_dwordx4 v[200:203], v[116:117], off offset:512
	global_load_dwordx4 v[204:207], v[116:117], off offset:576
	global_load_dwordx4 v[208:211], v[118:119], off
	global_load_dwordx4 v[212:215], v[118:119], off offset:64
	global_load_dwordx4 v[216:219], v[118:119], off offset:512
	global_load_dwordx4 v[220:223], v[118:119], off offset:576
	global_load_dwordx4 v[224:227], v[112:113], off
	global_load_dwordx4 v[228:231], v[112:113], off offset:64
	global_load_dwordx4 v[124:127], v[112:113], off offset:512
	global_load_dwordx4 v[120:123], v[112:113], off offset:576
	global_load_dwordx4 v[108:111], v[114:115], off
	global_load_dwordx4 v[104:107], v[114:115], off offset:64
	global_load_dwordx4 v[100:103], v[114:115], off offset:512
	global_load_dwordx4 v[96:99], v[114:115], off offset:576
	s_waitcnt vmcnt(0)
	v_pk_fma_f32 v[62:63], v[62:63], v[158:159], v[194:195]
	v_pk_fma_f32 v[60:61], v[60:61], v[160:161], v[192:193]
	global_store_dwordx4 v[116:117], v[60:63], off
	v_pk_fma_f32 v[58:59], v[58:59], v[154:155], v[198:199]
	v_pk_fma_f32 v[56:57], v[56:57], v[156:157], v[196:197]
	global_store_dwordx4 v[116:117], v[56:59], off offset:64
	v_pk_fma_f32 v[54:55], v[54:55], v[142:143], v[202:203]
	v_pk_fma_f32 v[52:53], v[52:53], v[152:153], v[200:201]
	global_store_dwordx4 v[116:117], v[52:55], off offset:512
	v_pk_fma_f32 v[50:51], v[50:51], v[138:139], v[206:207]
	v_pk_fma_f32 v[48:49], v[48:49], v[140:141], v[204:205]
	global_store_dwordx4 v[116:117], v[48:51], off offset:576
	v_pk_fma_f32 v[46:47], v[46:47], v[158:159], v[210:211]
	v_pk_fma_f32 v[44:45], v[44:45], v[160:161], v[208:209]
	global_store_dwordx4 v[118:119], v[44:47], off
	v_pk_fma_f32 v[42:43], v[42:43], v[154:155], v[214:215]
	v_pk_fma_f32 v[40:41], v[40:41], v[156:157], v[212:213]
	global_store_dwordx4 v[118:119], v[40:43], off offset:64
	v_pk_fma_f32 v[38:39], v[38:39], v[142:143], v[218:219]
	v_pk_fma_f32 v[36:37], v[36:37], v[152:153], v[216:217]
	global_store_dwordx4 v[118:119], v[36:39], off offset:512
	v_pk_fma_f32 v[34:35], v[34:35], v[138:139], v[222:223]
	v_pk_fma_f32 v[32:33], v[32:33], v[140:141], v[220:221]
	global_store_dwordx4 v[118:119], v[32:35], off offset:576
	v_pk_fma_f32 v[30:31], v[30:31], v[158:159], v[226:227]
	v_pk_fma_f32 v[28:29], v[28:29], v[160:161], v[224:225]
	global_store_dwordx4 v[112:113], v[28:31], off
	v_pk_fma_f32 v[26:27], v[26:27], v[154:155], v[230:231]
	v_pk_fma_f32 v[24:25], v[24:25], v[156:157], v[228:229]
	global_store_dwordx4 v[112:113], v[24:27], off offset:64
	v_pk_fma_f32 v[22:23], v[22:23], v[142:143], v[126:127]
	v_pk_fma_f32 v[20:21], v[20:21], v[152:153], v[124:125]
	global_store_dwordx4 v[112:113], v[20:23], off offset:512
	v_pk_fma_f32 v[18:19], v[18:19], v[138:139], v[122:123]
	v_pk_fma_f32 v[16:17], v[16:17], v[140:141], v[120:121]
	global_store_dwordx4 v[112:113], v[16:19], off offset:576
	v_pk_fma_f32 v[14:15], v[14:15], v[158:159], v[110:111]
	v_pk_fma_f32 v[12:13], v[12:13], v[160:161], v[108:109]
	global_store_dwordx4 v[114:115], v[12:15], off
	v_pk_fma_f32 v[10:11], v[10:11], v[154:155], v[106:107]
	v_pk_fma_f32 v[8:9], v[8:9], v[156:157], v[104:105]
	global_store_dwordx4 v[114:115], v[8:11], off offset:64
	v_pk_fma_f32 v[6:7], v[6:7], v[142:143], v[102:103]
	v_pk_fma_f32 v[4:5], v[4:5], v[152:153], v[100:101]
	global_store_dwordx4 v[114:115], v[4:7], off offset:512
	v_pk_fma_f32 v[2:3], v[2:3], v[138:139], v[98:99]
	v_pk_fma_f32 v[0:1], v[0:1], v[140:141], v[96:97]
	global_store_dwordx4 v[114:115], v[0:3], off offset:576
	s_mov_b64 s[14:15], s[6:7]
	s_and_b64 vcc, exec, s[4:5]
	s_cbranch_vccz .LBB0_363
	s_waitcnt vmcnt(0)
	s_mov_b32 s44, s77
	s_cmpk_gt_u32 s3, 0xff
	v_readlane_b32 s30, v254, 45
	v_readlane_b32 s34, v254, 46
	s_cbranch_scc1 .LBB0_378
	s_barrier
